# stack29: prep chunk-state products read all B fragments up front and double-buffer the A fragment (on top of stack27)
# speedup vs baseline: 1.0074x; 1.0074x over previous
; DI float bf2f(unsigned h) { return __uint_as_float(h << 16); }
; DI unsigned short f2bf(float f) { return (unsigned short)(pg8::cvt_pk_bf16(f, 0.f) & 0xffffu); }
; DI void prep_unit(const Params& P, int layer, int b, int c, char* lds, int tid) {
;     ...
;     for (int g = 0; g < 2; ++g) {
; #pragma unroll
;         for (int i = 0; i < 4; ++i) { const int q = tid + 512 * i, l = q & 127, n0 = (q >> 7) * 8;
;             const u32x4 v = *(const u32x4*)(SSDB + (size_t)(R0 + l) * 768 + 256 + 128 * g + n0);
;             bf16_t* d = BT + n0 * SP + l;
;             d[0] = (bf16_t)(v.x & 0xffffu); d[SP] = (bf16_t)(v.x >> 16); d[2 * SP] = (bf16_t)(v.y & 0xffffu); d[3 * SP] = (bf16_t)(v.y >> 16);
;             d[4 * SP] = (bf16_t)(v.z & 0xffffu); d[5 * SP] = (bf16_t)(v.z >> 16); d[6 * SP] = (bf16_t)(v.w & 0xffffu); d[7 * SP] = (bf16_t)(v.w >> 16); }
; #pragma unroll
;         for (int hs = 0; hs < 2; ++hs) { const int h = 2 * g + hs;
; #pragma unroll
;             for (int i = 0; i < 2; ++i) { const int q = tid + 512 * i, l = q & 127, p0 = (q >> 7) * 8;
;                 const u32x4 v = *(const u32x4*)(SSDB + (size_t)(R0 + l) * 768 + 64 * h + p0);
;                 const float f = dtl[h * CH + l] * expf(acs[h * CH + CH - 1] - acs[h * CH + l]);
;                 bf16_t* d = XT[hs] + p0 * SP + l;
;                 d[0] = f2bf(bf2f(v.x & 0xffffu) * f); d[SP] = f2bf(bf2f(v.x >> 16) * f); d[2 * SP] = f2bf(bf2f(v.y & 0xffffu) * f); d[3 * SP] = f2bf(bf2f(v.y >> 16) * f);
;                 d[4 * SP] = f2bf(bf2f(v.z & 0xffffu) * f); d[5 * SP] = f2bf(bf2f(v.z >> 16) * f); d[6 * SP] = f2bf(bf2f(v.w & 0xffffu) * f); d[7 * SP] = f2bf(bf2f(v.w >> 16) * f); } }
.LBB0_201:
	s_lshl_b32 s62, s5, 8
	v_lshl_add_u64 v[6:7], v[18:19], 0, s[62:63]
	v_lshl_add_u64 v[8:9], v[6:7], 0, v[82:83]
	s_lshl_b32 s100, s5, 1
	s_or_b32 s100, s100, 1
	s_lshl_b32 s100, s100, 7
	s_mov_b32 s101, s63
	v_lshl_add_u64 v[14:15], v[6:7], 0, v[84:85]
	global_load_dwordx4 v[224:227], v[8:9], off offset:512
	global_load_dwordx4 v[228:231], v[14:15], off offset:512
	v_lshl_add_u64 v[16:17], v[42:43], 1, v[6:7]
	global_load_dwordx4 v[232:235], v[16:17], off offset:512
	v_lshl_add_u64 v[16:17], v[44:45], 1, v[6:7]
	global_load_dwordx4 v[244:247], v[16:17], off offset:512
	global_load_dwordx4 v[248:251], v[8:9], off
	global_load_dwordx4 v[252:255], v[14:15], off
	v_lshl_add_u64 v[16:17], v[18:19], 0, s[100:101]
	v_lshl_add_u64 v[14:15], v[16:17], 0, v[82:83]
	global_load_dwordx4 v[90:93], v[14:15], off
	v_lshl_add_u64 v[14:15], v[16:17], 0, v[84:85]
	global_load_dwordx4 v[94:97], v[14:15], off
	v_add_u32_e32 v10, v160, v162
	v_add_u32_e32 v12, v160, v163
	s_lshl_b32 s2, s5, 10
	s_lshl_b32 s4, s5, 1
	v_add_u32_e32 v122, s4, v20
	v_ashrrev_i32_e32 v123, 31, v122
	s_waitcnt vmcnt(7)
	v_mov_b64_e32 v[2:3], v[224:225]
	v_mov_b64_e32 v[4:5], v[226:227]
	ds_write_b16 v10, v2 offset:34816
	ds_write_b16_d16_hi v10, v2 offset:35088
	ds_write_b16 v10, v3 offset:35360
	ds_write_b16_d16_hi v10, v3 offset:35632
	ds_write_b16 v10, v4 offset:35904
	ds_write_b16_d16_hi v10, v4 offset:36176
	ds_write_b16 v10, v5 offset:36448
	ds_write_b16_d16_hi v10, v5 offset:36720
	v_lshl_add_u64 v[10:11], v[6:7], 0, v[84:85]
	s_waitcnt vmcnt(6)
	v_mov_b64_e32 v[2:3], v[228:229]
	v_mov_b64_e32 v[4:5], v[230:231]
	ds_write_b16 v12, v2 offset:34816
	ds_write_b16_d16_hi v12, v2 offset:35088
	ds_write_b16 v12, v3 offset:35360
	ds_write_b16_d16_hi v12, v3 offset:35632
	ds_write_b16 v12, v4 offset:35904
	ds_write_b16_d16_hi v12, v4 offset:36176
	ds_write_b16 v12, v5 offset:36448
	ds_write_b16_d16_hi v12, v5 offset:36720
	v_lshl_add_u64 v[2:3], v[42:43], 1, v[6:7]
	s_waitcnt vmcnt(5)
	v_mov_b64_e32 v[2:3], v[232:233]
	v_mov_b64_e32 v[4:5], v[234:235]
	ds_write_b16 v29, v2 offset:34816
	ds_write_b16_d16_hi v29, v2 offset:35088
	ds_write_b16 v29, v3 offset:35360
	ds_write_b16_d16_hi v29, v3 offset:35632
	ds_write_b16 v29, v4 offset:35904
	ds_write_b16_d16_hi v29, v4 offset:36176
	ds_write_b16 v29, v5 offset:36448
	ds_write_b16_d16_hi v29, v5 offset:36720
	v_lshl_add_u64 v[2:3], v[44:45], 1, v[6:7]
	v_lshlrev_b32_e32 v6, 2, v159
	s_waitcnt vmcnt(4)
	v_mov_b64_e32 v[2:3], v[244:245]
	v_mov_b64_e32 v[4:5], v[246:247]
	ds_write_b16 v172, v2 offset:34816
	ds_write_b16_d16_hi v172, v2 offset:35088
	ds_write_b16 v172, v3 offset:35360
	ds_write_b16_d16_hi v172, v3 offset:35632
	ds_write_b16 v172, v4 offset:35904
	ds_write_b16_d16_hi v172, v4 offset:36176
	ds_write_b16 v172, v5 offset:36448
	ds_write_b16_d16_hi v172, v5 offset:36720
	v_or_b32_e32 v2, s2, v6
	v_add_u32_e32 v7, s19, v2
	v_add_u32_e32 v12, s20, v2
	s_add_i32 s2, s20, s2
	v_mov_b32_e32 v9, s2
	ds_read_b32 v8, v7
	ds_read_b32 v13, v9 offset:508
	ds_read_b32 v14, v12
	s_or_b32 s2, s4, 1
	s_lshl_b32 s62, s2, 7
	s_lshl_b32 s2, s2, 9
	s_mov_b64 s[4:5], 0x8000
	s_waitcnt lgkmcnt(0)
	v_sub_f32_e32 v13, v13, v14
	v_mul_f32_e32 v14, 0x3fb8aa3b, v13
	v_fma_f32 v15, v13, s11, -v14
	v_rndne_f32_e32 v16, v14
	v_fmac_f32_e32 v15, 0x32a5705f, v13
	v_sub_f32_e32 v14, v14, v16
	v_add_f32_e32 v14, v14, v15
	v_exp_f32_e32 v14, v14
	v_cvt_i32_f32_e32 v15, v16
	v_cmp_ngt_f32_e32 vcc, s0, v13
	v_ldexp_f32 v14, v14, v15
	s_nop 0
	v_cndmask_b32_e32 v14, 0, v14, vcc
	v_cmp_nlt_f32_e32 vcc, s1, v13
	s_nop 1
	v_cndmask_b32_e32 v13, v206, v14, vcc
	v_mul_f32_e32 v8, v8, v13
	s_waitcnt vmcnt(3)
	v_mov_b64_e32 v[2:3], v[248:249]
	v_mov_b64_e32 v[4:5], v[250:251]
	v_lshlrev_b32_e32 v13, 16, v2
	v_and_b32_e32 v2, 0xffff0000, v2
	v_mul_f32_e32 v13, v8, v13
	v_mul_f32_e32 v2, v8, v2
	v_cvt_pk_bf16_f32 v13, v13, v1
	ds_write_b16 v164, v13
	v_cvt_pk_bf16_f32 v2, v2, v1
	ds_write_b16 v164, v2 offset:272
	v_lshlrev_b32_e32 v2, 16, v3
	v_mul_f32_e32 v2, v8, v2
	v_cvt_pk_bf16_f32 v2, v2, v1
	ds_write_b16 v164, v2 offset:544
	v_and_b32_e32 v2, 0xffff0000, v3
	v_mul_f32_e32 v2, v8, v2
	v_cvt_pk_bf16_f32 v2, v2, v1
	ds_write_b16 v164, v2 offset:816
	v_lshlrev_b32_e32 v2, 16, v4
	v_mul_f32_e32 v2, v8, v2
	v_cvt_pk_bf16_f32 v2, v2, v1
	ds_write_b16 v164, v2 offset:1088
	v_and_b32_e32 v2, 0xffff0000, v4
	v_mul_f32_e32 v2, v8, v2
	v_cvt_pk_bf16_f32 v2, v2, v1
	ds_write_b16 v164, v2 offset:1360
	v_lshlrev_b32_e32 v2, 16, v5
	v_mul_f32_e32 v2, v8, v2
	v_cvt_pk_bf16_f32 v2, v2, v1
	ds_write_b16 v164, v2 offset:1632
	v_and_b32_e32 v2, 0xffff0000, v5
	v_mul_f32_e32 v2, v8, v2
	v_cvt_pk_bf16_f32 v2, v2, v1
	ds_write_b16 v164, v2 offset:1904
	ds_read_b32 v7, v7
	ds_read_b32 v8, v9 offset:508
	ds_read_b32 v9, v12
	s_waitcnt lgkmcnt(0)
	v_sub_f32_e32 v8, v8, v9
	v_mul_f32_e32 v9, 0x3fb8aa3b, v8
	v_fma_f32 v10, v8, s11, -v9
	v_rndne_f32_e32 v11, v9
	v_fmac_f32_e32 v10, 0x32a5705f, v8
	v_sub_f32_e32 v9, v9, v11
	v_add_f32_e32 v9, v9, v10
	v_exp_f32_e32 v9, v9
	v_cvt_i32_f32_e32 v10, v11
	v_cmp_ngt_f32_e32 vcc, s0, v8
	v_ldexp_f32 v9, v9, v10
	s_nop 0
	v_cndmask_b32_e32 v9, 0, v9, vcc
	v_cmp_nlt_f32_e32 vcc, s1, v8
	s_nop 1
	v_cndmask_b32_e32 v8, v206, v9, vcc
	v_mul_f32_e32 v7, v7, v8
	s_waitcnt vmcnt(2)
; DI float bf2f(unsigned h) { return __uint_as_float(h << 16); }
; DI unsigned short f2bf(float f) { return (unsigned short)(pg8::cvt_pk_bf16(f, 0.f) & 0xffffu); }
; DI void prep_unit(const Params& P, int layer, int b, int c, char* lds, int tid) {
;     ...
;         for (int hs = 0; hs < 2; ++hs) { const int h = 2 * g + hs;
; #pragma unroll
;             for (int i = 0; i < 2; ++i) { const int q = tid + 512 * i, l = q & 127, p0 = (q >> 7) * 8;
;                 const u32x4 v = *(const u32x4*)(SSDB + (size_t)(R0 + l) * 768 + 64 * h + p0);
;                 const float f = dtl[h * CH + l] * expf(acs[h * CH + CH - 1] - acs[h * CH + l]);
;                 bf16_t* d = XT[hs] + p0 * SP + l;
;                 d[0] = f2bf(bf2f(v.x & 0xffffu) * f); d[SP] = f2bf(bf2f(v.x >> 16) * f); d[2 * SP] = f2bf(bf2f(v.y & 0xffffu) * f); d[3 * SP] = f2bf(bf2f(v.y >> 16) * f);
;                 d[4 * SP] = f2bf(bf2f(v.z & 0xffffu) * f); d[5 * SP] = f2bf(bf2f(v.z >> 16) * f); d[6 * SP] = f2bf(bf2f(v.w & 0xffffu) * f); d[7 * SP] = f2bf(bf2f(v.w >> 16) * f); } }
;         __syncthreads();
	v_mov_b64_e32 v[2:3], v[252:253]
	v_mov_b64_e32 v[4:5], v[254:255]
	v_lshlrev_b32_e32 v8, 16, v2
	v_and_b32_e32 v2, 0xffff0000, v2
	v_mul_f32_e32 v8, v7, v8
	v_mul_f32_e32 v2, v7, v2
	v_cvt_pk_bf16_f32 v8, v8, v1
	ds_write_b16 v165, v8
	v_cvt_pk_bf16_f32 v2, v2, v1
	ds_write_b16 v165, v2 offset:272
	v_lshlrev_b32_e32 v2, 16, v3
	v_mul_f32_e32 v2, v7, v2
	v_cvt_pk_bf16_f32 v2, v2, v1
	ds_write_b16 v165, v2 offset:544
	v_and_b32_e32 v2, 0xffff0000, v3
	v_mul_f32_e32 v2, v7, v2
	v_cvt_pk_bf16_f32 v2, v2, v1
	ds_write_b16 v165, v2 offset:816
	v_lshlrev_b32_e32 v2, 16, v4
	v_mul_f32_e32 v2, v7, v2
	v_cvt_pk_bf16_f32 v2, v2, v1
	ds_write_b16 v165, v2 offset:1088
	v_and_b32_e32 v2, 0xffff0000, v4
	v_mul_f32_e32 v2, v7, v2
	v_cvt_pk_bf16_f32 v2, v2, v1
	ds_write_b16 v165, v2 offset:1360
	v_lshlrev_b32_e32 v2, 16, v5
	v_mul_f32_e32 v2, v7, v2
	v_cvt_pk_bf16_f32 v2, v2, v1
	ds_write_b16 v165, v2 offset:1632
	v_and_b32_e32 v2, 0xffff0000, v5
	v_mul_f32_e32 v2, v7, v2
	v_cvt_pk_bf16_f32 v2, v2, v1
	ds_write_b16 v165, v2 offset:1904
	v_lshl_add_u64 v[2:3], v[18:19], 0, s[62:63]
	v_or_b32_e32 v5, s2, v6
	v_lshl_add_u64 v[6:7], v[2:3], 0, v[82:83]
	s_add_i32 s2, s20, s2
	v_add_u32_e32 v4, s19, v5
	v_mov_b32_e32 v6, s2
	v_add_u32_e32 v5, s20, v5
	ds_read_b32 v7, v4
	ds_read_b32 v12, v6 offset:508
	ds_read_b32 v13, v5
	v_lshl_add_u64 v[2:3], v[2:3], 0, v[84:85]
	s_waitcnt lgkmcnt(0)
	v_sub_f32_e32 v12, v12, v13
	v_mul_f32_e32 v13, 0x3fb8aa3b, v12
	v_fma_f32 v14, v12, s11, -v13
	v_rndne_f32_e32 v15, v13
	v_fmac_f32_e32 v14, 0x32a5705f, v12
	v_sub_f32_e32 v13, v13, v15
	v_add_f32_e32 v13, v13, v14
	v_exp_f32_e32 v13, v13
	v_cvt_i32_f32_e32 v14, v15
	v_cmp_ngt_f32_e32 vcc, s0, v12
	v_ldexp_f32 v13, v13, v14
	s_nop 0
	v_cndmask_b32_e32 v13, 0, v13, vcc
	v_cmp_nlt_f32_e32 vcc, s1, v12
	s_nop 1
	v_cndmask_b32_e32 v12, v206, v13, vcc
	v_mul_f32_e32 v7, v7, v12
	s_waitcnt vmcnt(1)
	v_mov_b64_e32 v[8:9], v[90:91]
	v_mov_b64_e32 v[10:11], v[92:93]
	v_lshlrev_b32_e32 v12, 16, v8
	v_and_b32_e32 v8, 0xffff0000, v8
	v_mul_f32_e32 v12, v7, v12
	v_mul_f32_e32 v8, v7, v8
	v_cvt_pk_bf16_f32 v12, v12, v1
	ds_write_b16 v166, v12
	v_cvt_pk_bf16_f32 v8, v8, v1
	ds_write_b16 v166, v8 offset:272
	v_lshlrev_b32_e32 v8, 16, v9
	v_mul_f32_e32 v8, v7, v8
	v_cvt_pk_bf16_f32 v8, v8, v1
	ds_write_b16 v166, v8 offset:544
	v_and_b32_e32 v8, 0xffff0000, v9
	v_mul_f32_e32 v8, v7, v8
	v_cvt_pk_bf16_f32 v8, v8, v1
	ds_write_b16 v166, v8 offset:816
	v_lshlrev_b32_e32 v8, 16, v10
	v_mul_f32_e32 v8, v7, v8
	v_cvt_pk_bf16_f32 v8, v8, v1
	ds_write_b16 v166, v8 offset:1088
	v_and_b32_e32 v8, 0xffff0000, v10
	v_mul_f32_e32 v8, v7, v8
	v_cvt_pk_bf16_f32 v8, v8, v1
	ds_write_b16 v166, v8 offset:1360
	v_lshlrev_b32_e32 v8, 16, v11
	v_mul_f32_e32 v8, v7, v8
	v_cvt_pk_bf16_f32 v8, v8, v1
	ds_write_b16 v166, v8 offset:1632
	v_and_b32_e32 v8, 0xffff0000, v11
	v_mul_f32_e32 v7, v7, v8
	v_cvt_pk_bf16_f32 v7, v7, v1
	ds_write_b16 v166, v7 offset:1904
	ds_read_b32 v2, v4
	ds_read_b32 v3, v6 offset:508
	ds_read_b32 v4, v5
	s_waitcnt lgkmcnt(0)
	v_sub_f32_e32 v3, v3, v4
	v_mul_f32_e32 v4, 0x3fb8aa3b, v3
	v_fma_f32 v5, v3, s11, -v4
	v_rndne_f32_e32 v6, v4
	v_fmac_f32_e32 v5, 0x32a5705f, v3
	v_sub_f32_e32 v4, v4, v6
	v_add_f32_e32 v4, v4, v5
	v_exp_f32_e32 v4, v4
	v_cvt_i32_f32_e32 v5, v6
	v_cmp_ngt_f32_e32 vcc, s0, v3
	v_ldexp_f32 v4, v4, v5
	s_nop 0
	v_cndmask_b32_e32 v4, 0, v4, vcc
	v_cmp_nlt_f32_e32 vcc, s1, v3
	s_nop 1
	v_cndmask_b32_e32 v3, v206, v4, vcc
	v_mul_f32_e32 v2, v2, v3
	s_and_b64 vcc, exec, s[38:39]
	s_mov_b64 s[38:39], 0
	s_waitcnt vmcnt(0)
	v_mov_b64_e32 v[8:9], v[94:95]
	v_mov_b64_e32 v[10:11], v[96:97]
	v_lshlrev_b32_e32 v3, 16, v8
	v_mul_f32_e32 v3, v2, v3
	v_cvt_pk_bf16_f32 v3, v3, v1
	ds_write_b16 v167, v3
	v_and_b32_e32 v3, 0xffff0000, v8
	v_mul_f32_e32 v3, v2, v3
	v_cvt_pk_bf16_f32 v3, v3, v1
	ds_write_b16 v167, v3 offset:272
	v_lshlrev_b32_e32 v3, 16, v9
	v_mul_f32_e32 v3, v2, v3
	v_cvt_pk_bf16_f32 v3, v3, v1
	ds_write_b16 v167, v3 offset:544
	v_and_b32_e32 v3, 0xffff0000, v9
	v_mul_f32_e32 v3, v2, v3
	v_cvt_pk_bf16_f32 v3, v3, v1
	ds_write_b16 v167, v3 offset:816
	v_lshlrev_b32_e32 v3, 16, v10
	v_mul_f32_e32 v3, v2, v3
	v_cvt_pk_bf16_f32 v3, v3, v1
	ds_write_b16 v167, v3 offset:1088
	v_and_b32_e32 v3, 0xffff0000, v10
	v_mul_f32_e32 v3, v2, v3
	v_cvt_pk_bf16_f32 v3, v3, v1
	ds_write_b16 v167, v3 offset:1360
	v_lshlrev_b32_e32 v3, 16, v11
	v_mul_f32_e32 v3, v2, v3
	v_cvt_pk_bf16_f32 v3, v3, v1
	ds_write_b16 v167, v3 offset:1632
	v_and_b32_e32 v3, 0xffff0000, v11
	v_mul_f32_e32 v2, v2, v3
	v_cvt_pk_bf16_f32 v2, v2, v1
	ds_write_b16 v167, v2 offset:1904
	s_waitcnt lgkmcnt(0)
	s_barrier
; DI int crow(int r, int h) { return (r & 3) + 8 * (r >> 2) + 4 * h; }
; #define MFMA32(a, b, c) __builtin_amdgcn_mfma_f32_32x32x16_bf16((a), (b), (c), 0, 0, 0)
; DI void prep_unit(const Params& P, int layer, int b, int c, char* lds, int tid) {
;     ...
; #pragma unroll
;         for (int hs = 0; hs < 2; ++hs) { const int h = 2 * g + hs;
;             f32x16 acc = {};
; #pragma unroll
;             for (int ks = 0; ks < 8; ++ks) { const bf16x8 a = *(const bf16x8*)(XT[hs] + (32 * pb + r) * SP + 16 * ks + 8 * hh); const bf16x8 bb = *(const bf16x8*)(BT + (32 * nb + r) * SP + 16 * ks + 8 * hh);
;                 acc = MFMA32(a, bb, acc); }
;             float* sp = ST + ((size_t)((b * NCHUNK + c) * 4 + h) * 64) * 128;
; #pragma unroll
;             for (int i = 0; i < 16; ++i) sp[(size_t)(32 * pb + crow(i, hh)) * 128 + 32 * nb + r] = acc[i]; }
;         __syncthreads();
	ds_read_b128 v[2:5], v168
	ds_read_b128 v[86:89], v168 offset:32
	ds_read_b128 v[90:93], v161 offset:34816
	ds_read_b128 v[94:97], v161 offset:34848
	ds_read_b128 v[98:101], v161 offset:34880
	ds_read_b128 v[102:105], v161 offset:34912
	ds_read_b128 v[106:109], v161 offset:34944
	ds_read_b128 v[110:113], v161 offset:34976
	ds_read_b128 v[114:117], v161 offset:35008
	ds_read_b128 v[118:121], v161 offset:35040
	ds_read_b128 v[224:227], v168 offset:64
	s_waitcnt lgkmcnt(8)
	v_mfma_f32_32x32x16_bf16 v[2:17], v[2:5], v[90:93], 0
	s_waitcnt lgkmcnt(7)
	v_mfma_f32_32x32x16_bf16 v[2:17], v[86:89], v[94:97], v[2:17]
	ds_read_b128 v[86:89], v168 offset:96
	s_waitcnt lgkmcnt(1)
	v_mfma_f32_32x32x16_bf16 v[2:17], v[224:227], v[98:101], v[2:17]
	ds_read_b128 v[224:227], v168 offset:128
	s_waitcnt lgkmcnt(1)
	v_mfma_f32_32x32x16_bf16 v[2:17], v[86:89], v[102:105], v[2:17]
	ds_read_b128 v[86:89], v168 offset:160
	s_waitcnt lgkmcnt(1)
	v_mfma_f32_32x32x16_bf16 v[2:17], v[224:227], v[106:109], v[2:17]
	ds_read_b128 v[224:227], v168 offset:192
	s_waitcnt lgkmcnt(1)
	v_mfma_f32_32x32x16_bf16 v[2:17], v[86:89], v[110:113], v[2:17]
	ds_read_b128 v[86:89], v168 offset:224
	s_waitcnt lgkmcnt(1)
	v_mfma_f32_32x32x16_bf16 v[2:17], v[224:227], v[114:117], v[2:17]
	s_waitcnt lgkmcnt(0)
	v_mfma_f32_32x32x16_bf16 v[2:17], v[86:89], v[118:121], v[2:17]
	v_lshlrev_b64 v[86:87], 15, v[122:123]
	v_lshl_add_u64 v[122:123], v[40:41], 0, v[86:87]
	v_lshl_add_u64 v[86:87], v[122:123], 0, v[38:39]
	s_nop 8
	global_store_dword v[86:87], v2, off
	global_store_dword v[86:87], v3, off offset:512
	global_store_dword v[86:87], v4, off offset:1024
	global_store_dword v[86:87], v5, off offset:1536
	v_lshl_add_u64 v[2:3], v[122:123], 0, v[46:47]
	global_store_dword v[2:3], v6, off
	v_lshl_add_u64 v[2:3], v[122:123], 0, v[48:49]
	global_store_dword v[2:3], v7, off
	v_lshl_add_u64 v[2:3], v[122:123], 0, v[50:51]
	global_store_dword v[2:3], v8, off
	v_lshl_add_u64 v[2:3], v[122:123], 0, v[52:53]
	global_store_dword v[2:3], v9, off
	v_lshl_add_u64 v[2:3], v[122:123], 0, v[54:55]
	global_store_dword v[2:3], v10, off
	v_lshl_add_u64 v[2:3], v[122:123], 0, v[56:57]
	global_store_dword v[2:3], v11, off
	v_lshl_add_u64 v[2:3], v[122:123], 0, v[58:59]
	global_store_dword v[2:3], v12, off
	v_lshl_add_u64 v[2:3], v[122:123], 0, v[60:61]
	global_store_dword v[2:3], v13, off
	v_lshl_add_u64 v[2:3], v[122:123], 0, v[62:63]
	global_store_dword v[2:3], v14, off
	v_lshl_add_u64 v[2:3], v[122:123], 0, v[64:65]
	global_store_dword v[2:3], v15, off
	v_lshl_add_u64 v[2:3], v[122:123], 0, v[66:67]
	global_store_dword v[2:3], v16, off
	v_lshl_add_u64 v[2:3], v[122:123], 0, v[68:69]
	global_store_dword v[2:3], v17, off
	ds_read_b128 v[2:5], v169
	ds_read_b128 v[86:89], v169 offset:32
	ds_read_b128 v[224:227], v169 offset:64
	s_waitcnt lgkmcnt(2)
	v_mfma_f32_32x32x16_bf16 v[2:17], v[2:5], v[90:93], 0
	s_waitcnt lgkmcnt(1)
	v_mfma_f32_32x32x16_bf16 v[2:17], v[86:89], v[94:97], v[2:17]
	ds_read_b128 v[86:89], v169 offset:96
	s_waitcnt lgkmcnt(1)
	v_mfma_f32_32x32x16_bf16 v[2:17], v[224:227], v[98:101], v[2:17]
	ds_read_b128 v[224:227], v169 offset:128
	s_waitcnt lgkmcnt(1)
	v_mfma_f32_32x32x16_bf16 v[2:17], v[86:89], v[102:105], v[2:17]
	ds_read_b128 v[86:89], v169 offset:160
	s_waitcnt lgkmcnt(1)
	v_mfma_f32_32x32x16_bf16 v[2:17], v[224:227], v[106:109], v[2:17]
	ds_read_b128 v[224:227], v169 offset:192
	s_waitcnt lgkmcnt(1)
	v_mfma_f32_32x32x16_bf16 v[2:17], v[86:89], v[110:113], v[2:17]
	ds_read_b128 v[86:89], v169 offset:224
	s_waitcnt lgkmcnt(1)
	v_mfma_f32_32x32x16_bf16 v[2:17], v[224:227], v[114:117], v[2:17]
	s_waitcnt lgkmcnt(0)
	v_mfma_f32_32x32x16_bf16 v[2:17], v[86:89], v[118:121], v[2:17]
	v_lshl_add_u64 v[86:87], v[122:123], 0, s[4:5]
	v_lshl_add_u64 v[88:89], v[86:87], 0, v[38:39]
	s_nop 9
	global_store_dword v[88:89], v2, off
	global_store_dword v[88:89], v3, off offset:512
	global_store_dword v[88:89], v4, off offset:1024
	global_store_dword v[88:89], v5, off offset:1536
	v_lshl_add_u64 v[2:3], v[86:87], 0, v[46:47]
	global_store_dword v[2:3], v6, off
	v_lshl_add_u64 v[2:3], v[86:87], 0, v[48:49]
	global_store_dword v[2:3], v7, off
	v_lshl_add_u64 v[2:3], v[86:87], 0, v[50:51]
	global_store_dword v[2:3], v8, off
	v_lshl_add_u64 v[2:3], v[86:87], 0, v[52:53]
	global_store_dword v[2:3], v9, off
	v_lshl_add_u64 v[2:3], v[86:87], 0, v[54:55]
	global_store_dword v[2:3], v10, off
	v_lshl_add_u64 v[2:3], v[86:87], 0, v[56:57]
	global_store_dword v[2:3], v11, off
	v_lshl_add_u64 v[2:3], v[86:87], 0, v[58:59]
	global_store_dword v[2:3], v12, off
	v_lshl_add_u64 v[2:3], v[86:87], 0, v[60:61]
	global_store_dword v[2:3], v13, off
	v_lshl_add_u64 v[2:3], v[86:87], 0, v[62:63]
	global_store_dword v[2:3], v14, off
	v_lshl_add_u64 v[2:3], v[86:87], 0, v[64:65]
	global_store_dword v[2:3], v15, off
	v_lshl_add_u64 v[2:3], v[86:87], 0, v[66:67]
	global_store_dword v[2:3], v16, off
	v_lshl_add_u64 v[2:3], v[86:87], 0, v[68:69]
	s_mov_b32 s5, 1
	global_store_dword v[2:3], v17, off
	s_barrier
	s_cbranch_vccnz .LBB0_201
	s_add_i32 s78, s78, s30
	s_cmpk_gt_i32 s78, 0xff
	s_cbranch_scc0 .LBB0_182
